# GEMM accumulator zero-init before the K loops: 176 register pairs cleared with v_mov_b64 instead of two v_mov_b32 each (code shrinks by 11 x 64 bytes); on top of v168
# baseline (speedup 1.0000x reference)
.LBB0_141:
	s_ashr_i32 s51, s50, 31
	s_lshl_b64 s[2:3], s[50:51], 19
	s_add_u32 s22, s77, s2
	s_addc_u32 s23, s81, s3
	s_and_b64 s[2:3], s[6:7], exec
	s_cselect_b32 s2, s23, s9
	s_cselect_b32 s4, s22, s8
	s_add_u32 s6, s10, 0x40080
	s_addc_u32 s7, s11, 0
	s_add_u32 s5, s8, 0x100
	v_mov_b32_e32 v34, 0
	s_addc_u32 s20, s9, 0
	s_mov_b32 s21, -2
	v_mov_b32_e32 v35, v34
	v_mov_b32_e32 v36, v34
	v_mov_b32_e32 v37, v34
	v_mov_b32_e32 v38, v34
	v_mov_b32_e32 v39, v34
	s_waitcnt vmcnt(0)
	v_mov_b32_e32 v142, v34
	v_mov_b32_e32 v143, v34
	v_mov_b32_e32 v144, v34
	v_mov_b32_e32 v145, v34
	v_mov_b32_e32 v126, v34
	v_mov_b32_e32 v127, v34
	v_mov_b32_e32 v128, v34
	v_mov_b32_e32 v129, v34
	v_mov_b32_e32 v134, v34
	v_mov_b32_e32 v135, v34
	v_mov_b32_e32 v136, v34
	v_mov_b32_e32 v137, v34
	v_mov_b32_e32 v146, v34
	v_mov_b32_e32 v147, v34
	v_mov_b32_e32 v148, v34
	v_mov_b32_e32 v149, v34
	v_mov_b32_e32 v124, v34
	v_mov_b32_e32 v125, v34
	v_mov_b32_e32 v130, v34
	v_mov_b32_e32 v131, v34
	v_mov_b32_e32 v132, v34
	v_mov_b32_e32 v133, v34
	v_mov_b32_e32 v138, v34
	v_mov_b32_e32 v139, v34
	v_mov_b32_e32 v140, v34
	v_mov_b32_e32 v141, v34
	v_mov_b64_e32 v[2:3], 0
	v_mov_b64_e32 v[4:5], 0
	v_mov_b64_e32 v[6:7], 0
	v_mov_b64_e32 v[8:9], 0
	v_mov_b64_e32 v[10:11], 0
	v_mov_b64_e32 v[12:13], 0
	v_mov_b64_e32 v[18:19], 0
	v_mov_b64_e32 v[20:21], 0
	v_mov_b64_e32 v[30:31], 0
	v_mov_b64_e32 v[32:33], 0
	v_mov_b64_e32 v[40:41], 0
	v_mov_b64_e32 v[42:43], 0
	v_mov_b64_e32 v[44:45], 0
	v_mov_b64_e32 v[46:47], 0
	v_mov_b64_e32 v[48:49], 0
	v_mov_b64_e32 v[50:51], 0
	v_mov_b64_e32 v[52:53], 0
	v_mov_b64_e32 v[54:55], 0
	v_mov_b64_e32 v[56:57], 0
	v_mov_b64_e32 v[58:59], 0
	v_mov_b64_e32 v[60:61], 0
	v_mov_b64_e32 v[62:63], 0
	v_mov_b64_e32 v[64:65], 0
	v_mov_b64_e32 v[66:67], 0
	v_mov_b64_e32 v[68:69], 0
	v_mov_b64_e32 v[70:71], 0
	v_mov_b64_e32 v[72:73], 0
	v_mov_b64_e32 v[74:75], 0
	v_mov_b64_e32 v[76:77], 0
	v_mov_b64_e32 v[78:79], 0
	v_mov_b64_e32 v[80:81], 0
	v_mov_b64_e32 v[82:83], 0
	v_mov_b64_e32 v[84:85], 0
	v_mov_b64_e32 v[86:87], 0
	v_mov_b64_e32 v[88:89], 0
	v_mov_b64_e32 v[90:91], 0
	v_mov_b64_e32 v[92:93], 0
	v_mov_b64_e32 v[94:95], 0
	v_mov_b64_e32 v[96:97], 0
	v_mov_b64_e32 v[98:99], 0
	v_mov_b64_e32 v[100:101], 0
	v_mov_b64_e32 v[110:111], 0
	v_mov_b64_e32 v[112:113], 0
	v_mov_b64_e32 v[114:115], 0
	v_mov_b64_e32 v[116:117], 0
	v_mov_b64_e32 v[118:119], 0
	v_mov_b64_e32 v[120:121], 0
	v_mov_b64_e32 v[122:123], 0

.LBB0_191:
	s_ashr_i32 s45, s44, 31
	s_lshl_b64 s[2:3], s[44:45], 19
	s_add_u32 s46, s1, s2
	s_addc_u32 s47, s28, s3
	s_and_b64 s[2:3], s[4:5], exec
	s_cselect_b32 s38, s47, s7
	s_cselect_b32 s39, s46, s6
	s_ashr_i32 s43, s42, 31
	s_lshl_b64 s[2:3], s[42:43], 19
	s_add_u32 s48, s29, s2
	s_addc_u32 s49, s40, s3
	s_and_b64 s[2:3], s[4:5], exec
	s_cselect_b32 s2, s49, s9
	s_cselect_b32 s43, s48, s8
	s_add_u32 s6, s6, 0x40080
	s_addc_u32 s7, s7, 0
	s_add_u32 s45, s8, 0x100
	v_mov_b32_e32 v2, 0
	s_addc_u32 s84, s9, 0
	s_mov_b32 vcc_lo, -2
	v_mov_b32_e32 v3, v2
	v_mov_b32_e32 v4, v2
	v_mov_b32_e32 v5, v2
	v_mov_b32_e32 v6, v2
	v_mov_b32_e32 v7, v2
	v_mov_b32_e32 v8, v2
	v_mov_b32_e32 v9, v2
	v_mov_b32_e32 v22, v2
	v_mov_b32_e32 v23, v2
	v_mov_b32_e32 v24, v2
	v_mov_b32_e32 v25, v2
	v_mov_b32_e32 v26, v2
	v_mov_b32_e32 v27, v2
	v_mov_b32_e32 v28, v2
	v_mov_b32_e32 v29, v2
	v_mov_b32_e32 v38, v2
	v_mov_b32_e32 v39, v2
	s_waitcnt vmcnt(0)
	v_mov_b32_e32 v40, v2
	v_mov_b32_e32 v41, v2
	v_mov_b32_e32 v42, v2
	v_mov_b32_e32 v43, v2
	v_mov_b32_e32 v44, v2
	v_mov_b32_e32 v45, v2
	v_mov_b32_e32 v66, v2
	v_mov_b32_e32 v67, v2
	v_mov_b32_e32 v68, v2
	v_mov_b32_e32 v69, v2
	v_mov_b32_e32 v74, v2
	v_mov_b32_e32 v75, v2
	v_mov_b32_e32 v76, v2
	v_mov_b32_e32 v77, v2
	v_mov_b32_e32 v10, v2
	v_mov_b32_e32 v11, v2
	v_mov_b32_e32 v12, v2
	v_mov_b32_e32 v13, v2
	v_mov_b32_e32 v18, v2
	s_waitcnt lgkmcnt(0)
	v_mov_b32_e32 v19, v2
	v_mov_b32_e32 v124, v2
	v_mov_b32_e32 v125, v2
	v_mov_b32_e32 v134, v2
	v_mov_b32_e32 v135, v2
	v_mov_b32_e32 v136, v2
	v_mov_b32_e32 v137, v2
	v_mov_b32_e32 v138, v2
	v_mov_b32_e32 v139, v2
	v_mov_b32_e32 v140, v2
	v_mov_b32_e32 v141, v2
	v_mov_b32_e32 v126, v2
	v_mov_b32_e32 v127, v2
	v_mov_b32_e32 v128, v2
	v_mov_b32_e32 v129, v2
	v_mov_b32_e32 v130, v2
	v_mov_b32_e32 v131, v2
	v_mov_b32_e32 v132, v2
	v_mov_b32_e32 v133, v2
	v_mov_b32_e32 v142, v2
	v_mov_b32_e32 v143, v2
	v_mov_b32_e32 v144, v2
	v_mov_b32_e32 v145, v2
	v_mov_b32_e32 v146, v2
	v_mov_b32_e32 v147, v2
	v_mov_b32_e32 v148, v2
	v_mov_b32_e32 v149, v2
	v_mov_b64_e32 v[20:21], 0
	v_mov_b64_e32 v[30:31], 0
	v_mov_b64_e32 v[32:33], 0
	v_mov_b64_e32 v[34:35], 0
	v_mov_b64_e32 v[36:37], 0
	v_mov_b64_e32 v[46:47], 0
	v_mov_b64_e32 v[48:49], 0
	v_mov_b64_e32 v[50:51], 0
	v_mov_b64_e32 v[52:53], 0
	v_mov_b64_e32 v[78:79], 0
	v_mov_b64_e32 v[80:81], 0
	v_mov_b64_e32 v[82:83], 0
	v_mov_b64_e32 v[84:85], 0
	v_mov_b64_e32 v[86:87], 0
	v_mov_b64_e32 v[88:89], 0
	v_mov_b64_e32 v[90:91], 0
	v_mov_b64_e32 v[92:93], 0
	v_mov_b64_e32 v[94:95], 0
	v_mov_b64_e32 v[96:97], 0
	v_mov_b64_e32 v[98:99], 0
	v_mov_b64_e32 v[100:101], 0
	v_mov_b64_e32 v[102:103], 0
	v_mov_b64_e32 v[104:105], 0
	v_mov_b64_e32 v[106:107], 0
	v_mov_b64_e32 v[108:109], 0
	v_mov_b64_e32 v[110:111], 0
	v_mov_b64_e32 v[112:113], 0
	v_mov_b64_e32 v[114:115], 0
	v_mov_b64_e32 v[116:117], 0
	v_mov_b64_e32 v[118:119], 0
	v_mov_b64_e32 v[120:121], 0
	v_mov_b64_e32 v[122:123], 0

.LBB0_750:
	s_add_u32 s2, s36, 0x100
	v_mov_b32_e32 v2, 0
	s_addc_u32 s55, s37, 0
	s_mov_b32 s57, -2
	v_mov_b32_e32 v3, v2
	v_mov_b32_e32 v4, v2
	s_waitcnt lgkmcnt(0)
	v_mov_b32_e32 v5, v2
	v_mov_b32_e32 v122, v2
	v_mov_b32_e32 v123, v2
	v_mov_b32_e32 v124, v2
	v_mov_b32_e32 v125, v2
	v_mov_b32_e32 v134, v2
	v_mov_b32_e32 v135, v2
	v_mov_b32_e32 v136, v2
	v_mov_b32_e32 v137, v2
	v_mov_b32_e32 v138, v2
	v_mov_b32_e32 v139, v2
	v_mov_b32_e32 v140, v2
	v_mov_b32_e32 v141, v2
	v_mov_b32_e32 v126, v2
	v_mov_b32_e32 v127, v2
	v_mov_b32_e32 v128, v2
	v_mov_b32_e32 v129, v2
	v_mov_b32_e32 v130, v2
	v_mov_b32_e32 v131, v2
	v_mov_b32_e32 v132, v2
	v_mov_b32_e32 v133, v2
	v_mov_b32_e32 v142, v2
	v_mov_b32_e32 v143, v2
	v_mov_b32_e32 v144, v2
	v_mov_b32_e32 v145, v2
	v_mov_b32_e32 v146, v2
	v_mov_b32_e32 v147, v2
	v_mov_b32_e32 v148, v2
	v_mov_b32_e32 v149, v2
	v_mov_b64_e32 v[6:7], 0
	v_mov_b64_e32 v[8:9], 0
	v_mov_b64_e32 v[10:11], 0
	v_mov_b64_e32 v[12:13], 0
	v_mov_b64_e32 v[18:19], 0
	v_mov_b64_e32 v[20:21], 0
	v_mov_b64_e32 v[22:23], 0
	v_mov_b64_e32 v[24:25], 0
	v_mov_b64_e32 v[26:27], 0
	v_mov_b64_e32 v[28:29], 0
	v_mov_b64_e32 v[30:31], 0
	v_mov_b64_e32 v[32:33], 0
	v_mov_b64_e32 v[34:35], 0
	v_mov_b64_e32 v[36:37], 0
	v_mov_b64_e32 v[38:39], 0
	v_mov_b64_e32 v[40:41], 0
	v_mov_b64_e32 v[42:43], 0
	v_mov_b64_e32 v[44:45], 0
	v_mov_b64_e32 v[46:47], 0
	v_mov_b64_e32 v[48:49], 0
	v_mov_b64_e32 v[50:51], 0
	v_mov_b64_e32 v[52:53], 0
	v_mov_b64_e32 v[54:55], 0
	v_mov_b64_e32 v[56:57], 0
	v_mov_b64_e32 v[58:59], 0
	v_mov_b64_e32 v[60:61], 0
	v_mov_b64_e32 v[62:63], 0
	v_mov_b64_e32 v[64:65], 0
	v_mov_b64_e32 v[66:67], 0
	v_mov_b64_e32 v[68:69], 0
	v_mov_b64_e32 v[86:87], 0
	v_mov_b64_e32 v[88:89], 0
	v_mov_b64_e32 v[90:91], 0
	v_mov_b64_e32 v[92:93], 0
	v_mov_b64_e32 v[94:95], 0
	v_mov_b64_e32 v[96:97], 0
	v_mov_b64_e32 v[98:99], 0
	v_mov_b64_e32 v[100:101], 0
	v_mov_b64_e32 v[102:103], 0
	v_mov_b64_e32 v[104:105], 0
	v_mov_b64_e32 v[106:107], 0
	v_mov_b64_e32 v[108:109], 0
	v_mov_b64_e32 v[110:111], 0
	v_mov_b64_e32 v[112:113], 0
	v_mov_b64_e32 v[114:115], 0
	v_mov_b64_e32 v[116:117], 0
	v_mov_b64_e32 v[118:119], 0
	v_mov_b64_e32 v[120:121], 0

.LBB0_816:
	s_ashr_i32 s17, s16, 31
	s_lshl_b64 s[2:3], s[16:17], 19
	s_add_u32 s18, s96, s2
	s_addc_u32 s19, s97, s3
	s_and_b64 s[2:3], s[4:5], exec
	s_cselect_b32 s17, s19, s37
	s_cselect_b32 s47, s18, s36
	s_ashr_i32 s15, s14, 31
	s_lshl_b64 s[2:3], s[14:15], 19
	s_add_u32 s22, s51, s2
	s_addc_u32 s23, s52, s3
	s_and_b64 s[2:3], s[4:5], exec
	s_cselect_b32 s2, s23, s39
	s_cselect_b32 s15, s22, s38
	s_add_u32 s36, s36, 0x40080
	s_addc_u32 s37, s37, 0
	s_add_u32 s48, s38, 0x100
	v_mov_b32_e32 v2, 0
	s_addc_u32 s49, s39, 0
	s_mov_b32 s50, -2
	v_mov_b32_e32 v3, v2
	v_mov_b32_e32 v104, v2
	v_mov_b32_e32 v105, v2
	v_mov_b32_e32 v106, v2
	v_mov_b32_e32 v107, v2
	v_mov_b32_e32 v108, v2
	v_mov_b32_e32 v109, v2
	v_mov_b32_e32 v118, v2
	v_mov_b32_e32 v119, v2
	v_mov_b32_e32 v120, v2
	v_mov_b32_e32 v121, v2
	v_mov_b32_e32 v122, v2
	v_mov_b32_e32 v123, v2
	v_mov_b32_e32 v124, v2
	v_mov_b32_e32 v125, v2
	v_mov_b32_e32 v110, v2
	v_mov_b32_e32 v111, v2
	v_mov_b32_e32 v112, v2
	v_mov_b32_e32 v113, v2
	v_mov_b32_e32 v114, v2
	v_mov_b32_e32 v115, v2
	v_mov_b32_e32 v116, v2
	v_mov_b32_e32 v117, v2
	v_mov_b32_e32 v126, v2
	v_mov_b32_e32 v127, v2
	v_mov_b32_e32 v128, v2
	v_mov_b32_e32 v129, v2
	v_mov_b32_e32 v130, v2
	v_mov_b32_e32 v131, v2
	v_mov_b32_e32 v132, v2
	v_mov_b32_e32 v133, v2
	v_mov_b64_e32 v[4:5], 0
	v_mov_b64_e32 v[6:7], 0
	v_mov_b64_e32 v[8:9], 0
	v_mov_b64_e32 v[10:11], 0
	v_mov_b64_e32 v[12:13], 0
	v_mov_b64_e32 v[18:19], 0
	v_mov_b64_e32 v[20:21], 0
	v_mov_b64_e32 v[22:23], 0
	v_mov_b64_e32 v[24:25], 0
	v_mov_b64_e32 v[26:27], 0
	v_mov_b64_e32 v[28:29], 0
	v_mov_b64_e32 v[30:31], 0
	v_mov_b64_e32 v[32:33], 0
	v_mov_b64_e32 v[34:35], 0
	v_mov_b64_e32 v[36:37], 0
	v_mov_b64_e32 v[38:39], 0
	v_mov_b64_e32 v[40:41], 0
	v_mov_b64_e32 v[42:43], 0
	v_mov_b64_e32 v[44:45], 0
	v_mov_b64_e32 v[46:47], 0
	v_mov_b64_e32 v[48:49], 0
	v_mov_b64_e32 v[50:51], 0
	v_mov_b64_e32 v[52:53], 0
	v_mov_b64_e32 v[54:55], 0
	v_mov_b64_e32 v[56:57], 0
	v_mov_b64_e32 v[58:59], 0
	v_mov_b64_e32 v[60:61], 0
	v_mov_b64_e32 v[62:63], 0
	v_mov_b64_e32 v[64:65], 0
	v_mov_b64_e32 v[66:67], 0
	v_mov_b64_e32 v[68:69], 0
	v_mov_b64_e32 v[70:71], 0
	v_mov_b64_e32 v[72:73], 0
	v_mov_b64_e32 v[74:75], 0
	v_mov_b64_e32 v[76:77], 0
	v_mov_b64_e32 v[78:79], 0
	v_mov_b64_e32 v[80:81], 0
	v_mov_b64_e32 v[82:83], 0
	v_mov_b64_e32 v[84:85], 0
	v_mov_b64_e32 v[86:87], 0
	v_mov_b64_e32 v[88:89], 0
	v_mov_b64_e32 v[90:91], 0
	v_mov_b64_e32 v[92:93], 0
	v_mov_b64_e32 v[94:95], 0
	v_mov_b64_e32 v[96:97], 0
	v_mov_b64_e32 v[98:99], 0
	v_mov_b64_e32 v[100:101], 0
	v_mov_b64_e32 v[102:103], 0
